# speedup vs baseline: 1.0015x; 1.0015x over previous
; #define SCHED() __builtin_amdgcn_sched_barrier(0)
; #define GLOADS(KS, VS, t, slot) do { char* lb_ = shm + (slot) * 16384 + wid * 1024;                                  \
;     __builtin_amdgcn_global_load_lds((const unsigned*)((KS) + (size_t)(t) * 64 * PW), (unsigned*)(lb_), 16, 0, 0);    \
;     __builtin_amdgcn_global_load_lds((const unsigned*)((VS) + (t) * 64), (unsigned*)(lb_ + 8192), 16, 0, 0); } while (0)
; #define KFR(slot) do { const char* Kc = shm + (slot) * 16384;                                                      \
;     _Pragma("unroll") for (int d0 = 0; d0 < 4; ++d0) { fr_[d0 * 2] = *(const bf16x8*)(Kc + roff[d0]); fr_[d0 * 2 + 1] = *(const bf16x8*)(Kc + roff[d0] + 4096); } } while (0)
; __device__ __forceinline__ void gqa_items(const Params& p, int l, int L, char* shm, const int tid, const int local, const int G, const int nGQ) {
;     ...
;     for (int j = 0; j < NT; ++j) {
;       if (j + 2 < NT) { const int ns_ = (cur == 0) ? 2 : cur - 1; GLOADS(Ks, Vs, j + 2, ns_); }
;       SCHED(); KFR(cur); SCHED();
.Lgq_step:
	ds_read_b128 v[192:195], v224
	ds_read_b128 v[196:199], v224 offset:4096
	ds_read_b128 v[200:203], v225
	ds_read_b128 v[204:207], v225 offset:4096
	ds_read_b128 v[208:211], v226
	ds_read_b128 v[212:215], v226 offset:4096
	ds_read_b128 v[216:219], v227
	ds_read_b128 v[220:223], v227 offset:4096
	s_add_i32 s2, s15, 2
	s_cmp_ge_u32 s2, s96
	s_cbranch_scc1 .Lgq_nold
	s_xor_b32 s2, s14, 2
	s_lshl_b32 s2, s2, 14
	s_add_i32 s2, s7, s2
	s_mov_b32 m0, s2
	v_lshl_add_u64 v[228:229], s[58:59], 1, v[74:75]
	global_load_lds_dwordx4 v[78:79], off
	s_add_i32 m0, s2, 0x2000
	s_nop 0
	global_load_lds_dwordx4 v[228:229], off
	v_lshl_add_u64 v[78:79], v[78:79], 0, s[92:93]
	s_add_i32 s58, s58, 64
	s_add_i32 m0, s2, 0x4000
	v_lshl_add_u64 v[228:229], s[58:59], 1, v[74:75]
	global_load_lds_dwordx4 v[78:79], off
	s_add_i32 m0, s2, 0x6000
	s_nop 0
	global_load_lds_dwordx4 v[228:229], off
	v_lshl_add_u64 v[78:79], v[78:79], 0, s[92:93]
	s_add_i32 s58, s58, 64
